# skip the O-accumulator rescale (LDS alpha exchange + 32 packed multiplies) on the first tile of each attention loop, where O is still zero
# baseline (speedup 1.0000x reference)
.LBB0_142:
	v_exp_f32_e64 v130, -v118
	v_add_f32_e32 v128, v128, v118
	v_xor_b32_e32 v160, 0x80000000, v128
	v_mov_b32_e32 v161, v160
	v_mov_b32_e32 v162, v160
	v_mov_b32_e32 v163, v160
	v_mov_b32_e32 v164, v160
	v_mov_b32_e32 v165, v160
	v_mov_b32_e32 v166, v160
	v_mov_b32_e32 v167, v160
	v_mov_b32_e32 v168, v160
	v_mov_b32_e32 v169, v160
	v_mov_b32_e32 v170, v160
	v_mov_b32_e32 v171, v160
	v_mov_b32_e32 v172, v160
	v_mov_b32_e32 v173, v160
	v_mov_b32_e32 v174, v160
	v_mov_b32_e32 v175, v160
	v_pk_add_f32 v[80:81], v[80:81], v[118:119] op_sel_hi:[1,0] neg_lo:[0,1] neg_hi:[0,1]
	v_pk_add_f32 v[82:83], v[82:83], v[118:119] op_sel_hi:[1,0] neg_lo:[0,1] neg_hi:[0,1]
	v_cndmask_b32_e64 v130, v130, 0, s[70:71]
	v_pk_add_f32 v[84:85], v[84:85], v[118:119] op_sel_hi:[1,0] neg_lo:[0,1] neg_hi:[0,1]
	v_pk_add_f32 v[86:87], v[86:87], v[118:119] op_sel_hi:[1,0] neg_lo:[0,1] neg_hi:[0,1]
	v_pk_add_f32 v[88:89], v[88:89], v[118:119] op_sel_hi:[1,0] neg_lo:[0,1] neg_hi:[0,1]
	v_pk_add_f32 v[90:91], v[90:91], v[118:119] op_sel_hi:[1,0] neg_lo:[0,1] neg_hi:[0,1]
	v_pk_add_f32 v[92:93], v[92:93], v[118:119] op_sel_hi:[1,0] neg_lo:[0,1] neg_hi:[0,1]
	v_pk_add_f32 v[94:95], v[94:95], v[118:119] op_sel_hi:[1,0] neg_lo:[0,1] neg_hi:[0,1]
	v_sub_f32_e32 v79, v79, v118
	v_sub_f32_e32 v78, v78, v118
	v_sub_f32_e32 v77, v77, v118
	v_sub_f32_e32 v76, v76, v118
	v_sub_f32_e32 v75, v75, v118
	v_sub_f32_e32 v74, v74, v118
	v_sub_f32_e32 v73, v73, v118
	v_sub_f32_e32 v72, v72, v118
	v_sub_f32_e32 v71, v71, v118
	v_sub_f32_e32 v70, v70, v118
	v_sub_f32_e32 v69, v69, v118
	v_sub_f32_e32 v68, v68, v118
	v_sub_f32_e32 v67, v67, v118
	v_sub_f32_e32 v66, v66, v118
	v_sub_f32_e32 v65, v65, v118
	v_sub_f32_e32 v64, v64, v118
	s_and_b64 vcc, exec, s[70:71]
	s_cbranch_vccnz .LBB0_146
	v_cmp_gt_f32_e32 vcc, 1.0, v130
	s_cbranch_vccz .LBB0_146

.LBB0_160:
	v_exp_f32_e64 v132, -v120
	v_add_f32_e32 v130, v130, v120
	v_xor_b32_e32 v160, 0x80000000, v130
	v_mov_b32_e32 v161, v160
	v_mov_b32_e32 v162, v160
	v_mov_b32_e32 v163, v160
	v_mov_b32_e32 v164, v160
	v_mov_b32_e32 v165, v160
	v_mov_b32_e32 v166, v160
	v_mov_b32_e32 v167, v160
	v_mov_b32_e32 v168, v160
	v_mov_b32_e32 v169, v160
	v_mov_b32_e32 v170, v160
	v_mov_b32_e32 v171, v160
	v_mov_b32_e32 v172, v160
	v_mov_b32_e32 v173, v160
	v_mov_b32_e32 v174, v160
	v_mov_b32_e32 v175, v160
	v_pk_add_f32 v[80:81], v[80:81], v[120:121] op_sel_hi:[1,0] neg_lo:[0,1] neg_hi:[0,1]
	v_pk_add_f32 v[82:83], v[82:83], v[120:121] op_sel_hi:[1,0] neg_lo:[0,1] neg_hi:[0,1]
	v_cndmask_b32_e64 v132, v132, 0, s[24:25]
	v_pk_add_f32 v[84:85], v[84:85], v[120:121] op_sel_hi:[1,0] neg_lo:[0,1] neg_hi:[0,1]
	v_pk_add_f32 v[86:87], v[86:87], v[120:121] op_sel_hi:[1,0] neg_lo:[0,1] neg_hi:[0,1]
	v_pk_add_f32 v[88:89], v[88:89], v[120:121] op_sel_hi:[1,0] neg_lo:[0,1] neg_hi:[0,1]
	v_pk_add_f32 v[90:91], v[90:91], v[120:121] op_sel_hi:[1,0] neg_lo:[0,1] neg_hi:[0,1]
	v_pk_add_f32 v[92:93], v[92:93], v[120:121] op_sel_hi:[1,0] neg_lo:[0,1] neg_hi:[0,1]
	v_pk_add_f32 v[94:95], v[94:95], v[120:121] op_sel_hi:[1,0] neg_lo:[0,1] neg_hi:[0,1]
	v_sub_f32_e32 v79, v79, v120
	v_sub_f32_e32 v78, v78, v120
	v_sub_f32_e32 v77, v77, v120
	v_sub_f32_e32 v76, v76, v120
	v_sub_f32_e32 v75, v75, v120
	v_sub_f32_e32 v74, v74, v120
	v_sub_f32_e32 v73, v73, v120
	v_sub_f32_e32 v72, v72, v120
	v_sub_f32_e32 v71, v71, v120
	v_sub_f32_e32 v70, v70, v120
	v_sub_f32_e32 v69, v69, v120
	v_sub_f32_e32 v68, v68, v120
	v_sub_f32_e32 v67, v67, v120
	v_sub_f32_e32 v66, v66, v120
	v_sub_f32_e32 v65, v65, v120
	v_sub_f32_e32 v64, v64, v120
	s_and_b64 vcc, exec, s[24:25]
	s_cbranch_vccnz .LBB0_164
	v_cmp_gt_f32_e32 vcc, 1.0, v132
	s_cbranch_vccz .LBB0_164

.LBB0_179:
	v_exp_f32_e64 v169, -v156
	v_add_f32_e32 v167, v167, v156
	v_pk_add_f32 v[80:81], v[80:81], v[156:157] op_sel_hi:[1,0] neg_lo:[0,1] neg_hi:[0,1]
	v_pk_add_f32 v[82:83], v[82:83], v[156:157] op_sel_hi:[1,0] neg_lo:[0,1] neg_hi:[0,1]
	v_cndmask_b32_e64 v169, v169, 0, s[2:3]
	v_pk_add_f32 v[84:85], v[84:85], v[156:157] op_sel_hi:[1,0] neg_lo:[0,1] neg_hi:[0,1]
	v_pk_add_f32 v[86:87], v[86:87], v[156:157] op_sel_hi:[1,0] neg_lo:[0,1] neg_hi:[0,1]
	v_pk_add_f32 v[88:89], v[88:89], v[156:157] op_sel_hi:[1,0] neg_lo:[0,1] neg_hi:[0,1]
	v_pk_add_f32 v[90:91], v[90:91], v[156:157] op_sel_hi:[1,0] neg_lo:[0,1] neg_hi:[0,1]
	v_pk_add_f32 v[92:93], v[92:93], v[156:157] op_sel_hi:[1,0] neg_lo:[0,1] neg_hi:[0,1]
	v_pk_add_f32 v[94:95], v[94:95], v[156:157] op_sel_hi:[1,0] neg_lo:[0,1] neg_hi:[0,1]
	v_sub_f32_e32 v79, v79, v156
	v_sub_f32_e32 v78, v78, v156
	v_sub_f32_e32 v77, v77, v156
	v_sub_f32_e32 v76, v76, v156
	v_sub_f32_e32 v75, v75, v156
	v_sub_f32_e32 v74, v74, v156
	v_sub_f32_e32 v73, v73, v156
	v_sub_f32_e32 v72, v72, v156
	v_sub_f32_e32 v71, v71, v156
	v_sub_f32_e32 v70, v70, v156
	v_sub_f32_e32 v69, v69, v156
	v_sub_f32_e32 v68, v68, v156
	v_sub_f32_e32 v67, v67, v156
	v_sub_f32_e32 v66, v66, v156
	v_sub_f32_e32 v65, v65, v156
	v_sub_f32_e32 v64, v64, v156
	s_and_b64 vcc, exec, s[2:3]
	s_cbranch_vccnz .LBB0_183
	v_cmp_gt_f32_e32 vcc, 1.0, v169
	s_cbranch_vccz .LBB0_183
